# baseline (speedup 1.0000x reference)
;     ...
;     if (MODE == 0 || MODE == 3) {
;       char* ct = smem;
; #pragma unroll
;       for (int ai = 0; ai < 2; ++ai)
; #pragma unroll
;         for (int m = 0; m < 4; ++m) {
;           const int rloc = ai * HALF + wr * 64 + m * 16 + fr;
;           float rscale = 1.f;
;           if (MODE == 3) {
;             const long row = brow + rloc;
;             const float4 s0 = *(const float4*)(ssq + row * 8), s1 = *(const float4*)(ssq + row * 8 + 4);
;             rscale = rsqrtf((s0.x + s0.y + s0.z + s0.w + s1.x + s1.y + s1.z + s1.w) * (1.f / DM) + EPS);
;           }
; #pragma unroll
;           for (int bj = 0; bj < 2; ++bj)
; #pragma unroll
;             for (int n = 0; n < 2; ++n) {
;               const int cl = bj * HALF + wc * 32 + n * 16 + fq * 4;
;               f32x4 a = acc[ai][bj][m][n];
;               uint2 o;
;               o.x = pack2(a[0] * rscale, a[1] * rscale);
;               o.y = pack2(a[2] * rscale, a[3] * rscale);
;               *(uint2*)(ct + rloc * 528 + cl * 2) = o;
;             }
;         }
;       __syncthreads();
.Lp1_epi:
	v_and_b32_e32 v170, 15, v194
	v_bfe_u32 v171, v194, 4, 2
	v_bfe_u32 v172, v194, 6, 2
	v_lshrrev_b32_e32 v173, 8, v194
	v_lshl_or_b32 v173, v173, 6, v170
	v_lshlrev_b32_e32 v174, 6, v172
	v_lshl_add_u32 v174, v171, 3, v174
	v_mov_b32_e32 v175, 0x10020
	v_mov_b32_e32 v176, 0x8000
	v_cmp_gt_u32_e32 vcc, 62, v173
	v_mul_u32_u24_e32 v184, 0x210, v173
	v_cndmask_b32_e32 v179, v175, v176, vcc
	v_add3_u32 v184, v184, v174, v179
	v_add_u32_e32 v178, 16, v173
	v_cmp_gt_u32_e32 vcc, 62, v178
	v_mul_u32_u24_e32 v185, 0x210, v178
	v_cndmask_b32_e32 v179, v175, v176, vcc
	v_add3_u32 v185, v185, v174, v179
	v_add_u32_e32 v178, 32, v173
	v_cmp_gt_u32_e32 vcc, 62, v178
	v_mul_u32_u24_e32 v186, 0x210, v178
	v_cndmask_b32_e32 v179, v175, v176, vcc
	v_add3_u32 v186, v186, v174, v179
	v_add_u32_e32 v178, 48, v173
	v_cmp_gt_u32_e32 vcc, 62, v178
	v_mul_u32_u24_e32 v187, 0x210, v178
	v_cndmask_b32_e32 v179, v175, v176, vcc
	v_add3_u32 v187, v187, v174, v179
	v_lshrrev_b32_e32 v177, 5, v194
	v_and_b32_e32 v178, 31, v194
	v_mul_u32_u24_e32 v181, 0x210, v177
	v_lshl_add_u32 v181, v178, 4, v181
	v_add_u32_e32 v188, 48, v177
	v_cmp_gt_u32_e32 vcc, 62, v188
	v_cndmask_b32_e32 v179, v175, v176, vcc
	v_add_u32_e32 v189, 0x8000, v181
	v_add_u32_e32 v190, 0x6300, v181
	v_add_u32_e32 v190, v190, v179
	v_add_u32_e32 v191, 0x10020, v181
	s_lshl_b32 s36, s43, 1
	s_add_u32 s36, s76, s36
	s_addc_u32 s37, s77, 0
	v_add_u32_e32 v192, s42, v177
	v_lshlrev_b32_e32 v178, 4, v178
	v_mov_b32_e32 v179, 0
	v_lshl_add_u64 v[178:179], s[36:37], 0, v[178:179]
	s_movk_i32 s38, 0x3600
	v_mad_u64_u32 v[182:183], s[40:41], v192, s38, v[178:179]
	s_mov_b32 s44, 0x36000
	s_mov_b32 s45, 0
	v_cvt_pk_bf16_f32 v108, v108, v109
	v_cvt_pk_bf16_f32 v109, v110, v111
	v_cvt_pk_bf16_f32 v104, v104, v105
	v_cvt_pk_bf16_f32 v105, v106, v107
	ds_write2_b64 v184, v[108:109], v[104:105] offset1:4
	v_cvt_pk_bf16_f32 v124, v124, v125
	v_cvt_pk_bf16_f32 v125, v126, v127
	v_cvt_pk_bf16_f32 v120, v120, v121
	v_cvt_pk_bf16_f32 v121, v122, v123
	ds_write2_b64 v184, v[124:125], v[120:121] offset0:32 offset1:36
	v_cvt_pk_bf16_f32 v96, v96, v97
	v_cvt_pk_bf16_f32 v97, v98, v99
	v_cvt_pk_bf16_f32 v84, v84, v85
	v_cvt_pk_bf16_f32 v85, v86, v87
	ds_write2_b64 v185, v[96:97], v[84:85] offset1:4
	v_cvt_pk_bf16_f32 v116, v116, v117
	v_cvt_pk_bf16_f32 v117, v118, v119
	v_cvt_pk_bf16_f32 v112, v112, v113
	v_cvt_pk_bf16_f32 v113, v114, v115
	ds_write2_b64 v185, v[116:117], v[112:113] offset0:32 offset1:36
	v_cvt_pk_bf16_f32 v64, v64, v65
	v_cvt_pk_bf16_f32 v65, v66, v67
	v_cvt_pk_bf16_f32 v56, v56, v57
	v_cvt_pk_bf16_f32 v57, v58, v59
	ds_write2_b64 v186, v[64:65], v[56:57] offset1:4
	v_cvt_pk_bf16_f32 v100, v100, v101
	v_cvt_pk_bf16_f32 v101, v102, v103
	v_cvt_pk_bf16_f32 v88, v88, v89
	v_cvt_pk_bf16_f32 v89, v90, v91
	ds_write2_b64 v186, v[100:101], v[88:89] offset0:32 offset1:36
	v_cvt_pk_bf16_f32 v36, v36, v37
	v_cvt_pk_bf16_f32 v37, v38, v39
	v_cvt_pk_bf16_f32 v32, v32, v33
	v_cvt_pk_bf16_f32 v33, v34, v35
	ds_write2_b64 v187, v[36:37], v[32:33] offset1:4
	v_cvt_pk_bf16_f32 v68, v68, v69
	v_cvt_pk_bf16_f32 v69, v70, v71
	v_cvt_pk_bf16_f32 v60, v60, v61
	v_cvt_pk_bf16_f32 v61, v62, v63
	ds_write2_b64 v187, v[68:69], v[60:61] offset0:32 offset1:36
	s_waitcnt lgkmcnt(0)
	s_barrier
;     ...
; #pragma unroll
;           for (int bj = 0; bj < 2; ++bj)
; #pragma unroll
;             for (int n = 0; n < 2; ++n) {
;               const int cl = bj * HALF + wc * 32 + n * 16 + fq * 4;
;               f32x4 a = acc[ai][bj][m][n];
;               uint2 o;
;               o.x = pack2(a[0] * rscale, a[1] * rscale);
;               o.y = pack2(a[2] * rscale, a[3] * rscale);
;               *(uint2*)(ct + rloc * 528 + cl * 2) = o;
;             }
;         }
;       __syncthreads();
; #pragma unroll
;       for (int i = 0; i < 16; ++i) {
;         const int rloc = i * 16 + (tid_ >> 5), ch = tid_ & 31;
;         uint4 v = *(const uint4*)(ct + rloc * 528 + ch * 16);
;         typedef unsigned u32x4_t __attribute__((ext_vector_type(4)));
;         u32x4_t vv = {v.x, v.y, v.z, v.w};
;         __builtin_nontemporal_store(vv, (u32x4_t*)(Cb + (long)(brow + rloc) * ldc + bcol + ch * 8));
;       }
	ds_read_b128 v[222:225], v189
	ds_read_b128 v[226:229], v189 offset:8448
	ds_read_b128 v[230:233], v189 offset:16896
	ds_read_b128 v[234:237], v190
	v_lshl_add_u64 v[170:171], v[182:183], 0, s[44:45]
	v_lshl_add_u64 v[172:173], v[170:171], 0, s[44:45]
	v_lshl_add_u64 v[174:175], v[172:173], 0, s[44:45]
	v_lshl_add_u64 v[176:177], v[174:175], 0, s[44:45]
	s_waitcnt lgkmcnt(3)
	global_store_dwordx4 v[182:183], v[222:225], off nt
	s_waitcnt lgkmcnt(2)
	global_store_dwordx4 v[170:171], v[226:229], off nt
	s_waitcnt lgkmcnt(1)
	global_store_dwordx4 v[172:173], v[230:233], off nt
	s_waitcnt lgkmcnt(0)
	global_store_dwordx4 v[174:175], v[234:237], off nt
	s_nop 1
	v_mov_b64_e32 v[182:183], v[176:177]
	ds_read_b128 v[222:225], v191 offset:33792
	ds_read_b128 v[226:229], v191 offset:42240
	ds_read_b128 v[230:233], v191 offset:50688
	ds_read_b128 v[234:237], v191 offset:59136
	v_lshl_add_u64 v[170:171], v[182:183], 0, s[44:45]
	v_lshl_add_u64 v[172:173], v[170:171], 0, s[44:45]
	v_lshl_add_u64 v[174:175], v[172:173], 0, s[44:45]
	v_lshl_add_u64 v[176:177], v[174:175], 0, s[44:45]
	s_waitcnt lgkmcnt(3)
	global_store_dwordx4 v[182:183], v[222:225], off nt
	s_waitcnt lgkmcnt(2)
	global_store_dwordx4 v[170:171], v[226:229], off nt
	s_waitcnt lgkmcnt(1)
	global_store_dwordx4 v[172:173], v[230:233], off nt
	s_waitcnt lgkmcnt(0)
	global_store_dwordx4 v[174:175], v[234:237], off nt
	s_nop 1
	v_mov_b64_e32 v[182:183], v[176:177]
	s_barrier
	v_cvt_pk_bf16_f32 v76, v76, v77
	v_cvt_pk_bf16_f32 v77, v78, v79
	v_cvt_pk_bf16_f32 v72, v72, v73
	v_cvt_pk_bf16_f32 v73, v74, v75
	ds_write2_b64 v184, v[76:77], v[72:73] offset1:4
	v_cvt_pk_bf16_f32 v92, v92, v93
	v_cvt_pk_bf16_f32 v93, v94, v95
	v_cvt_pk_bf16_f32 v80, v80, v81
	v_cvt_pk_bf16_f32 v81, v82, v83
	ds_write2_b64 v184, v[92:93], v[80:81] offset0:32 offset1:36
	v_cvt_pk_bf16_f32 v44, v44, v45
	v_cvt_pk_bf16_f32 v45, v46, v47
	v_cvt_pk_bf16_f32 v40, v40, v41
	v_cvt_pk_bf16_f32 v41, v42, v43
	ds_write2_b64 v185, v[44:45], v[40:41] offset1:4
	v_cvt_pk_bf16_f32 v52, v52, v53
	v_cvt_pk_bf16_f32 v53, v54, v55
	v_cvt_pk_bf16_f32 v48, v48, v49
	v_cvt_pk_bf16_f32 v49, v50, v51
	ds_write2_b64 v185, v[52:53], v[48:49] offset0:32 offset1:36
	v_cvt_pk_bf16_f32 v20, v20, v21
	v_cvt_pk_bf16_f32 v21, v22, v23
	v_cvt_pk_bf16_f32 v16, v16, v17
	v_cvt_pk_bf16_f32 v17, v18, v19
	ds_write2_b64 v186, v[20:21], v[16:17] offset1:4
	v_cvt_pk_bf16_f32 v28, v28, v29
	v_cvt_pk_bf16_f32 v29, v30, v31
	v_cvt_pk_bf16_f32 v24, v24, v25
	v_cvt_pk_bf16_f32 v25, v26, v27
	ds_write2_b64 v186, v[28:29], v[24:25] offset0:32 offset1:36
	v_cvt_pk_bf16_f32 v4, v4, v5
	v_cvt_pk_bf16_f32 v5, v6, v7
	v_cvt_pk_bf16_f32 v0, v0, v1
	v_cvt_pk_bf16_f32 v1, v2, v3
	ds_write2_b64 v187, v[4:5], v[0:1] offset1:4
	v_cvt_pk_bf16_f32 v12, v12, v13
	v_cvt_pk_bf16_f32 v13, v14, v15
	v_cvt_pk_bf16_f32 v8, v8, v9
	v_cvt_pk_bf16_f32 v9, v10, v11
	ds_write2_b64 v187, v[12:13], v[8:9] offset0:32 offset1:36
	s_waitcnt lgkmcnt(0)
	s_barrier
	ds_read_b128 v[222:225], v189
	ds_read_b128 v[226:229], v189 offset:8448
	ds_read_b128 v[230:233], v189 offset:16896
	ds_read_b128 v[234:237], v190
	v_lshl_add_u64 v[170:171], v[182:183], 0, s[44:45]
	v_lshl_add_u64 v[172:173], v[170:171], 0, s[44:45]
	v_lshl_add_u64 v[174:175], v[172:173], 0, s[44:45]
	v_lshl_add_u64 v[176:177], v[174:175], 0, s[44:45]
	s_waitcnt lgkmcnt(3)
	global_store_dwordx4 v[182:183], v[222:225], off nt
	s_waitcnt lgkmcnt(2)
	global_store_dwordx4 v[170:171], v[226:229], off nt
	s_waitcnt lgkmcnt(1)
	global_store_dwordx4 v[172:173], v[230:233], off nt
	s_waitcnt lgkmcnt(0)
	global_store_dwordx4 v[174:175], v[234:237], off nt
	s_nop 1
	v_mov_b64_e32 v[182:183], v[176:177]
	ds_read_b128 v[222:225], v191 offset:33792
	ds_read_b128 v[226:229], v191 offset:42240
	ds_read_b128 v[230:233], v191 offset:50688
	ds_read_b128 v[234:237], v191 offset:59136
	v_lshl_add_u64 v[170:171], v[182:183], 0, s[44:45]
	v_lshl_add_u64 v[172:173], v[170:171], 0, s[44:45]
	v_lshl_add_u64 v[174:175], v[172:173], 0, s[44:45]
	v_lshl_add_u64 v[176:177], v[174:175], 0, s[44:45]
	s_waitcnt lgkmcnt(3)
	global_store_dwordx4 v[182:183], v[222:225], off nt
	s_waitcnt lgkmcnt(2)
	global_store_dwordx4 v[170:171], v[226:229], off nt
	s_waitcnt lgkmcnt(1)
	global_store_dwordx4 v[172:173], v[230:233], off nt
	s_waitcnt lgkmcnt(0)
	global_store_dwordx4 v[174:175], v[234:237], off nt
	s_nop 1
	v_mov_b64_e32 v[182:183], v[176:177]
	s_barrier
	s_cmp_eq_u32 s32, 1
	s_cbranch_scc1 .Lp1_hdr2
	s_branch .Lp1_exit

;     ...
;           const int rloc = ai * HALF + wr * 64 + m * 16 + fr;
;           float rscale = 1.f;
;           if (MODE == 3) {
;             const long row = brow + rloc;
;             const float4 s0 = *(const float4*)(ssq + row * 8), s1 = *(const float4*)(ssq + row * 8 + 4);
;             rscale = rsqrtf((s0.x + s0.y + s0.z + s0.w + s1.x + s1.y + s1.z + s1.w) * (1.f / DM) + EPS);
;           }
; #pragma unroll
;           for (int bj = 0; bj < 2; ++bj)
; #pragma unroll
;             for (int n = 0; n < 2; ++n) {
;               const int cl = bj * HALF + wc * 32 + n * 16 + fq * 4;
;               f32x4 a = acc[ai][bj][m][n];
;               uint2 o;
;               o.x = pack2(a[0] * rscale, a[1] * rscale);
;               o.y = pack2(a[2] * rscale, a[3] * rscale);
;               *(uint2*)(ct + rloc * 528 + cl * 2) = o;
;             }
;         }
;       __syncthreads();
.Lp6_sw1:
	v_add_f32_e32 v250, v250, v251
	v_add_f32_e32 v250, v250, v252
	v_add_f32_e32 v250, v250, v253
	v_and_b32_e32 v251, 0xff, v194
	v_lshrrev_b32_e32 v252, 8, v194
	v_lshl_or_b32 v251, v251, 1, v252
	v_lshlrev_b32_e32 v251, 2, v251
	v_add_u32_e32 v251, 0x20c00, v251
	ds_write_b32 v251, v250
	v_and_b32_e32 v170, 15, v194
	v_bfe_u32 v171, v194, 4, 2
	v_bfe_u32 v172, v194, 6, 2
	v_lshrrev_b32_e32 v173, 8, v194
	v_lshl_or_b32 v173, v173, 6, v170
	v_lshlrev_b32_e32 v174, 6, v172
	v_lshl_add_u32 v174, v171, 3, v174
	v_mov_b32_e32 v175, 0x10020
	v_mov_b32_e32 v176, 0x8000
	v_cmp_gt_u32_e32 vcc, 62, v173
	v_mul_u32_u24_e32 v184, 0x210, v173
	v_cndmask_b32_e32 v179, v175, v176, vcc
	v_add3_u32 v184, v184, v174, v179
	v_add_u32_e32 v178, 16, v173
	v_cmp_gt_u32_e32 vcc, 62, v178
	v_mul_u32_u24_e32 v185, 0x210, v178
	v_cndmask_b32_e32 v179, v175, v176, vcc
	v_add3_u32 v185, v185, v174, v179
	v_add_u32_e32 v178, 32, v173
	v_cmp_gt_u32_e32 vcc, 62, v178
	v_mul_u32_u24_e32 v186, 0x210, v178
	v_cndmask_b32_e32 v179, v175, v176, vcc
	v_add3_u32 v186, v186, v174, v179
	v_add_u32_e32 v178, 48, v173
	v_cmp_gt_u32_e32 vcc, 62, v178
	v_mul_u32_u24_e32 v187, 0x210, v178
	v_cndmask_b32_e32 v179, v175, v176, vcc
	v_add3_u32 v187, v187, v174, v179
	v_lshlrev_b32_e32 v180, 3, v173
	v_add_u32_e32 v180, 0x20c00, v180
	v_lshrrev_b32_e32 v177, 5, v194
	v_and_b32_e32 v178, 31, v194
	v_mul_u32_u24_e32 v181, 0x210, v177
	v_lshl_add_u32 v181, v178, 4, v181
	v_add_u32_e32 v188, 48, v177
	v_cmp_gt_u32_e32 vcc, 62, v188
	v_cndmask_b32_e32 v179, v175, v176, vcc
	v_add_u32_e32 v189, 0x8000, v181
	v_add_u32_e32 v190, 0x6300, v181
	v_add_u32_e32 v190, v190, v179
	v_add_u32_e32 v191, 0x10020, v181
	s_lshl_b32 s66, s71, 1
	s_add_u32 s66, s88, s66
	s_addc_u32 s67, s89, 0
	v_add_u32_e32 v192, s70, v177
	v_lshlrev_b32_e32 v178, 4, v178
	v_mov_b32_e32 v179, 0
	v_lshl_add_u64 v[178:179], s[66:67], 0, v[178:179]
	s_movk_i32 s63, 0x4000
	v_mad_u64_u32 v[182:183], s[68:69], v192, s63, v[178:179]
	s_mov_b32 s72, 0x40000
	s_mov_b32 s73, 0
	s_waitcnt lgkmcnt(0)
	s_barrier
	ds_read_b64 v[238:239], v180
	ds_read_b64 v[240:241], v180 offset:128
	ds_read_b64 v[242:243], v180 offset:256
	ds_read_b64 v[244:245], v180 offset:384
	s_waitcnt lgkmcnt(0)
	v_add_f32_e32 v238, v238, v239
	v_mul_f32_e32 v238, 0x3a000000, v238
	v_add_f32_e32 v238, 0x358637bd, v238
	v_rsq_f32_e32 v238, v238
	v_add_f32_e32 v240, v240, v241
	v_mul_f32_e32 v240, 0x3a000000, v240
	v_add_f32_e32 v240, 0x358637bd, v240
	v_rsq_f32_e32 v240, v240
	v_add_f32_e32 v242, v242, v243
	v_mul_f32_e32 v242, 0x3a000000, v242
	v_add_f32_e32 v242, 0x358637bd, v242
	v_rsq_f32_e32 v242, v242
	v_add_f32_e32 v244, v244, v245
	v_mul_f32_e32 v244, 0x3a000000, v244
	v_add_f32_e32 v244, 0x358637bd, v244
	v_rsq_f32_e32 v244, v244
	s_nop 0
	v_mul_f32_e32 v104, v104, v238
	v_mul_f32_e32 v105, v105, v238
	v_mul_f32_e32 v106, v106, v238
	v_mul_f32_e32 v107, v107, v238
	v_cvt_pk_bf16_f32 v104, v104, v105
	v_cvt_pk_bf16_f32 v105, v106, v107
	v_mul_f32_e32 v108, v108, v238
	v_mul_f32_e32 v109, v109, v238
	v_mul_f32_e32 v110, v110, v238
	v_mul_f32_e32 v111, v111, v238
	v_cvt_pk_bf16_f32 v108, v108, v109
	v_cvt_pk_bf16_f32 v109, v110, v111
	ds_write2_b64 v184, v[104:105], v[108:109] offset1:4
	v_mul_f32_e32 v120, v120, v238
	v_mul_f32_e32 v121, v121, v238
	v_mul_f32_e32 v122, v122, v238
	v_mul_f32_e32 v123, v123, v238
	v_cvt_pk_bf16_f32 v120, v120, v121
	v_cvt_pk_bf16_f32 v121, v122, v123
	v_mul_f32_e32 v124, v124, v238
	v_mul_f32_e32 v125, v125, v238
	v_mul_f32_e32 v126, v126, v238
	v_mul_f32_e32 v127, v127, v238
	v_cvt_pk_bf16_f32 v124, v124, v125
	v_cvt_pk_bf16_f32 v125, v126, v127
	ds_write2_b64 v184, v[120:121], v[124:125] offset0:32 offset1:36
	v_mul_f32_e32 v96, v96, v240
	v_mul_f32_e32 v97, v97, v240
	v_mul_f32_e32 v98, v98, v240
	v_mul_f32_e32 v99, v99, v240
	v_cvt_pk_bf16_f32 v96, v96, v97
	v_cvt_pk_bf16_f32 v97, v98, v99
	v_mul_f32_e32 v100, v100, v240
	v_mul_f32_e32 v101, v101, v240
	v_mul_f32_e32 v102, v102, v240
	v_mul_f32_e32 v103, v103, v240
	v_cvt_pk_bf16_f32 v100, v100, v101
	v_cvt_pk_bf16_f32 v101, v102, v103
	ds_write2_b64 v185, v[96:97], v[100:101] offset1:4
	v_mul_f32_e32 v112, v112, v240
	v_mul_f32_e32 v113, v113, v240
	v_mul_f32_e32 v114, v114, v240
	v_mul_f32_e32 v115, v115, v240
	v_cvt_pk_bf16_f32 v112, v112, v113
	v_cvt_pk_bf16_f32 v113, v114, v115
	v_mul_f32_e32 v116, v116, v240
	v_mul_f32_e32 v117, v117, v240
	v_mul_f32_e32 v118, v118, v240
	v_mul_f32_e32 v119, v119, v240
	v_cvt_pk_bf16_f32 v116, v116, v117
	v_cvt_pk_bf16_f32 v117, v118, v119
	ds_write2_b64 v185, v[112:113], v[116:117] offset0:32 offset1:36
	v_mul_f32_e32 v84, v84, v242
	v_mul_f32_e32 v85, v85, v242
	v_mul_f32_e32 v86, v86, v242
	v_mul_f32_e32 v87, v87, v242
	v_cvt_pk_bf16_f32 v84, v84, v85
	v_cvt_pk_bf16_f32 v85, v86, v87
	v_mul_f32_e32 v80, v80, v242
	v_mul_f32_e32 v81, v81, v242
	v_mul_f32_e32 v82, v82, v242
	v_mul_f32_e32 v83, v83, v242
	v_cvt_pk_bf16_f32 v80, v80, v81
	v_cvt_pk_bf16_f32 v81, v82, v83
	ds_write2_b64 v186, v[84:85], v[80:81] offset1:4
	v_mul_f32_e32 v92, v92, v242
	v_mul_f32_e32 v93, v93, v242
	v_mul_f32_e32 v94, v94, v242
	v_mul_f32_e32 v95, v95, v242
	v_cvt_pk_bf16_f32 v92, v92, v93
	v_cvt_pk_bf16_f32 v93, v94, v95
	v_mul_f32_e32 v88, v88, v242
	v_mul_f32_e32 v89, v89, v242
	v_mul_f32_e32 v90, v90, v242
	v_mul_f32_e32 v91, v91, v242
	v_cvt_pk_bf16_f32 v88, v88, v89
	v_cvt_pk_bf16_f32 v89, v90, v91
	ds_write2_b64 v186, v[92:93], v[88:89] offset0:32 offset1:36
	v_mul_f32_e32 v76, v76, v244
	v_mul_f32_e32 v77, v77, v244
	v_mul_f32_e32 v78, v78, v244
	v_mul_f32_e32 v79, v79, v244
	v_cvt_pk_bf16_f32 v76, v76, v77
	v_cvt_pk_bf16_f32 v77, v78, v79
	v_mul_f32_e32 v72, v72, v244
	v_mul_f32_e32 v73, v73, v244
	v_mul_f32_e32 v74, v74, v244
	v_mul_f32_e32 v75, v75, v244
	v_cvt_pk_bf16_f32 v72, v72, v73
	v_cvt_pk_bf16_f32 v73, v74, v75
	ds_write2_b64 v187, v[76:77], v[72:73] offset1:4
	v_mul_f32_e32 v68, v68, v244
	v_mul_f32_e32 v69, v69, v244
	v_mul_f32_e32 v70, v70, v244
	v_mul_f32_e32 v71, v71, v244
	v_cvt_pk_bf16_f32 v68, v68, v69
	v_cvt_pk_bf16_f32 v69, v70, v71
	v_mul_f32_e32 v64, v64, v244
	v_mul_f32_e32 v65, v65, v244
	v_mul_f32_e32 v66, v66, v244
	v_mul_f32_e32 v67, v67, v244
	v_cvt_pk_bf16_f32 v64, v64, v65
	v_cvt_pk_bf16_f32 v65, v66, v67
	ds_write2_b64 v187, v[68:69], v[64:65] offset0:32 offset1:36
	s_waitcnt lgkmcnt(0)
	s_barrier
;     ...
;           const int rloc = ai * HALF + wr * 64 + m * 16 + fr;
;           float rscale = 1.f;
;           if (MODE == 3) {
;             const long row = brow + rloc;
;             const float4 s0 = *(const float4*)(ssq + row * 8), s1 = *(const float4*)(ssq + row * 8 + 4);
;             rscale = rsqrtf((s0.x + s0.y + s0.z + s0.w + s1.x + s1.y + s1.z + s1.w) * (1.f / DM) + EPS);
;           }
; #pragma unroll
;           for (int bj = 0; bj < 2; ++bj)
; #pragma unroll
;             for (int n = 0; n < 2; ++n) {
;               const int cl = bj * HALF + wc * 32 + n * 16 + fq * 4;
;               f32x4 a = acc[ai][bj][m][n];
;               uint2 o;
;               o.x = pack2(a[0] * rscale, a[1] * rscale);
;               o.y = pack2(a[2] * rscale, a[3] * rscale);
;               *(uint2*)(ct + rloc * 528 + cl * 2) = o;
;             }
;         }
;       __syncthreads();
; #pragma unroll
;       for (int i = 0; i < 16; ++i) {
;         const int rloc = i * 16 + (tid_ >> 5), ch = tid_ & 31;
;         uint4 v = *(const uint4*)(ct + rloc * 528 + ch * 16);
;         typedef unsigned u32x4_t __attribute__((ext_vector_type(4)));
;         u32x4_t vv = {v.x, v.y, v.z, v.w};
;         __builtin_nontemporal_store(vv, (u32x4_t*)(Cb + (long)(brow + rloc) * ldc + bcol + ch * 8));
;       }
	ds_read_b128 v[222:225], v189
	ds_read_b128 v[226:229], v189 offset:8448
	ds_read_b128 v[230:233], v189 offset:16896
	ds_read_b128 v[234:237], v190
	v_lshl_add_u64 v[170:171], v[182:183], 0, s[72:73]
	v_lshl_add_u64 v[172:173], v[170:171], 0, s[72:73]
	v_lshl_add_u64 v[174:175], v[172:173], 0, s[72:73]
	v_lshl_add_u64 v[176:177], v[174:175], 0, s[72:73]
	s_waitcnt lgkmcnt(3)
	global_store_dwordx4 v[182:183], v[222:225], off nt
	s_waitcnt lgkmcnt(2)
	global_store_dwordx4 v[170:171], v[226:229], off nt
	s_waitcnt lgkmcnt(1)
	global_store_dwordx4 v[172:173], v[230:233], off nt
	s_waitcnt lgkmcnt(0)
	global_store_dwordx4 v[174:175], v[234:237], off nt
	s_nop 1
	v_mov_b64_e32 v[182:183], v[176:177]
	ds_read_b128 v[222:225], v191 offset:33792
	ds_read_b128 v[226:229], v191 offset:42240
	ds_read_b128 v[230:233], v191 offset:50688
	ds_read_b128 v[234:237], v191 offset:59136
	v_lshl_add_u64 v[170:171], v[182:183], 0, s[72:73]
	v_lshl_add_u64 v[172:173], v[170:171], 0, s[72:73]
	v_lshl_add_u64 v[174:175], v[172:173], 0, s[72:73]
	v_lshl_add_u64 v[176:177], v[174:175], 0, s[72:73]
	s_waitcnt lgkmcnt(3)
	global_store_dwordx4 v[182:183], v[222:225], off nt
	s_waitcnt lgkmcnt(2)
	global_store_dwordx4 v[170:171], v[226:229], off nt
	s_waitcnt lgkmcnt(1)
	global_store_dwordx4 v[172:173], v[230:233], off nt
	s_waitcnt lgkmcnt(0)
	global_store_dwordx4 v[174:175], v[234:237], off nt
	s_nop 1
	v_mov_b64_e32 v[182:183], v[176:177]
	s_barrier
	ds_read_b64 v[238:239], v180 offset:1024
	ds_read_b64 v[240:241], v180 offset:1152
	ds_read_b64 v[242:243], v180 offset:1280
	ds_read_b64 v[244:245], v180 offset:1408
	s_waitcnt lgkmcnt(0)
	v_add_f32_e32 v238, v238, v239
	v_mul_f32_e32 v238, 0x3a000000, v238
	v_add_f32_e32 v238, 0x358637bd, v238
	v_rsq_f32_e32 v238, v238
	v_add_f32_e32 v240, v240, v241
	v_mul_f32_e32 v240, 0x3a000000, v240
	v_add_f32_e32 v240, 0x358637bd, v240
	v_rsq_f32_e32 v240, v240
	v_add_f32_e32 v242, v242, v243
	v_mul_f32_e32 v242, 0x3a000000, v242
	v_add_f32_e32 v242, 0x358637bd, v242
	v_rsq_f32_e32 v242, v242
	v_add_f32_e32 v244, v244, v245
	v_mul_f32_e32 v244, 0x3a000000, v244
	v_add_f32_e32 v244, 0x358637bd, v244
	v_rsq_f32_e32 v244, v244
	s_nop 0
	v_mul_f32_e32 v52, v52, v238
	v_mul_f32_e32 v53, v53, v238
	v_mul_f32_e32 v54, v54, v238
	v_mul_f32_e32 v55, v55, v238
	v_cvt_pk_bf16_f32 v52, v52, v53
	v_cvt_pk_bf16_f32 v53, v54, v55
	v_mul_f32_e32 v48, v48, v238
	v_mul_f32_e32 v49, v49, v238
	v_mul_f32_e32 v50, v50, v238
	v_mul_f32_e32 v51, v51, v238
	v_cvt_pk_bf16_f32 v48, v48, v49
	v_cvt_pk_bf16_f32 v49, v50, v51
	ds_write2_b64 v184, v[52:53], v[48:49] offset1:4
	v_mul_f32_e32 v60, v60, v238
	v_mul_f32_e32 v61, v61, v238
	v_mul_f32_e32 v62, v62, v238
	v_mul_f32_e32 v63, v63, v238
	v_cvt_pk_bf16_f32 v60, v60, v61
	v_cvt_pk_bf16_f32 v61, v62, v63
	v_mul_f32_e32 v56, v56, v238
	v_mul_f32_e32 v57, v57, v238
	v_mul_f32_e32 v58, v58, v238
	v_mul_f32_e32 v59, v59, v238
	v_cvt_pk_bf16_f32 v56, v56, v57
	v_cvt_pk_bf16_f32 v57, v58, v59
	ds_write2_b64 v184, v[60:61], v[56:57] offset0:32 offset1:36
	v_mul_f32_e32 v36, v36, v240
	v_mul_f32_e32 v37, v37, v240
	v_mul_f32_e32 v38, v38, v240
	v_mul_f32_e32 v39, v39, v240
	v_cvt_pk_bf16_f32 v36, v36, v37
	v_cvt_pk_bf16_f32 v37, v38, v39
	v_mul_f32_e32 v32, v32, v240
	v_mul_f32_e32 v33, v33, v240
	v_mul_f32_e32 v34, v34, v240
	v_mul_f32_e32 v35, v35, v240
	v_cvt_pk_bf16_f32 v32, v32, v33
	v_cvt_pk_bf16_f32 v33, v34, v35
	ds_write2_b64 v185, v[36:37], v[32:33] offset1:4
	v_mul_f32_e32 v44, v44, v240
	v_mul_f32_e32 v45, v45, v240
	v_mul_f32_e32 v46, v46, v240
	v_mul_f32_e32 v47, v47, v240
	v_cvt_pk_bf16_f32 v44, v44, v45
	v_cvt_pk_bf16_f32 v45, v46, v47
	v_mul_f32_e32 v40, v40, v240
	v_mul_f32_e32 v41, v41, v240
	v_mul_f32_e32 v42, v42, v240
	v_mul_f32_e32 v43, v43, v240
	v_cvt_pk_bf16_f32 v40, v40, v41
	v_cvt_pk_bf16_f32 v41, v42, v43
	ds_write2_b64 v185, v[44:45], v[40:41] offset0:32 offset1:36
	v_mul_f32_e32 v20, v20, v242
	v_mul_f32_e32 v21, v21, v242
	v_mul_f32_e32 v22, v22, v242
	v_mul_f32_e32 v23, v23, v242
	v_cvt_pk_bf16_f32 v20, v20, v21
	v_cvt_pk_bf16_f32 v21, v22, v23
	v_mul_f32_e32 v16, v16, v242
	v_mul_f32_e32 v17, v17, v242
	v_mul_f32_e32 v18, v18, v242
	v_mul_f32_e32 v19, v19, v242
	v_cvt_pk_bf16_f32 v16, v16, v17
	v_cvt_pk_bf16_f32 v17, v18, v19
	ds_write2_b64 v186, v[20:21], v[16:17] offset1:4
	v_mul_f32_e32 v28, v28, v242
	v_mul_f32_e32 v29, v29, v242
	v_mul_f32_e32 v30, v30, v242
	v_mul_f32_e32 v31, v31, v242
	v_cvt_pk_bf16_f32 v28, v28, v29
	v_cvt_pk_bf16_f32 v29, v30, v31
	v_mul_f32_e32 v24, v24, v242
	v_mul_f32_e32 v25, v25, v242
	v_mul_f32_e32 v26, v26, v242
	v_mul_f32_e32 v27, v27, v242
	v_cvt_pk_bf16_f32 v24, v24, v25
	v_cvt_pk_bf16_f32 v25, v26, v27
	ds_write2_b64 v186, v[28:29], v[24:25] offset0:32 offset1:36
	v_mul_f32_e32 v8, v8, v244
	v_mul_f32_e32 v9, v9, v244
	v_mul_f32_e32 v10, v10, v244
	v_mul_f32_e32 v11, v11, v244
	v_cvt_pk_bf16_f32 v8, v8, v9
	v_cvt_pk_bf16_f32 v9, v10, v11
	v_mul_f32_e32 v0, v0, v244
	v_mul_f32_e32 v1, v1, v244
	v_mul_f32_e32 v2, v2, v244
	v_mul_f32_e32 v3, v3, v244
	v_cvt_pk_bf16_f32 v0, v0, v1
	v_cvt_pk_bf16_f32 v1, v2, v3
	ds_write2_b64 v187, v[8:9], v[0:1] offset1:4
	v_mul_f32_e32 v12, v12, v244
	v_mul_f32_e32 v13, v13, v244
	v_mul_f32_e32 v14, v14, v244
	v_mul_f32_e32 v15, v15, v244
	v_cvt_pk_bf16_f32 v12, v12, v13
	v_cvt_pk_bf16_f32 v13, v14, v15
	v_mul_f32_e32 v4, v4, v244
	v_mul_f32_e32 v5, v5, v244
	v_mul_f32_e32 v6, v6, v244
	v_mul_f32_e32 v7, v7, v244
	v_cvt_pk_bf16_f32 v4, v4, v5
	v_cvt_pk_bf16_f32 v5, v6, v7
	ds_write2_b64 v187, v[12:13], v[4:5] offset0:32 offset1:36
	s_waitcnt lgkmcnt(0)
	s_barrier
;     ...
; #pragma unroll
;       for (int i = 0; i < 16; ++i) {
;         const int rloc = i * 16 + (tid_ >> 5), ch = tid_ & 31;
;         uint4 v = *(const uint4*)(ct + rloc * 528 + ch * 16);
;         typedef unsigned u32x4_t __attribute__((ext_vector_type(4)));
;         u32x4_t vv = {v.x, v.y, v.z, v.w};
;         __builtin_nontemporal_store(vv, (u32x4_t*)(Cb + (long)(brow + rloc) * ldc + bcol + ch * 8));
;       }
	ds_read_b128 v[222:225], v189
	ds_read_b128 v[226:229], v189 offset:8448
	ds_read_b128 v[230:233], v189 offset:16896
	ds_read_b128 v[234:237], v190
	v_lshl_add_u64 v[170:171], v[182:183], 0, s[72:73]
	v_lshl_add_u64 v[172:173], v[170:171], 0, s[72:73]
	v_lshl_add_u64 v[174:175], v[172:173], 0, s[72:73]
	v_lshl_add_u64 v[176:177], v[174:175], 0, s[72:73]
	s_waitcnt lgkmcnt(3)
	global_store_dwordx4 v[182:183], v[222:225], off nt
	s_waitcnt lgkmcnt(2)
	global_store_dwordx4 v[170:171], v[226:229], off nt
	s_waitcnt lgkmcnt(1)
	global_store_dwordx4 v[172:173], v[230:233], off nt
	s_waitcnt lgkmcnt(0)
	global_store_dwordx4 v[174:175], v[234:237], off nt
	s_nop 1
	v_mov_b64_e32 v[182:183], v[176:177]
	ds_read_b128 v[222:225], v191 offset:33792
	ds_read_b128 v[226:229], v191 offset:42240
	ds_read_b128 v[230:233], v191 offset:50688
	ds_read_b128 v[234:237], v191 offset:59136
	v_lshl_add_u64 v[170:171], v[182:183], 0, s[72:73]
	v_lshl_add_u64 v[172:173], v[170:171], 0, s[72:73]
	v_lshl_add_u64 v[174:175], v[172:173], 0, s[72:73]
	v_lshl_add_u64 v[176:177], v[174:175], 0, s[72:73]
	s_waitcnt lgkmcnt(3)
	global_store_dwordx4 v[182:183], v[222:225], off nt
	s_waitcnt lgkmcnt(2)
	global_store_dwordx4 v[170:171], v[226:229], off nt
	s_waitcnt lgkmcnt(1)
	global_store_dwordx4 v[172:173], v[230:233], off nt
	s_waitcnt lgkmcnt(0)
	global_store_dwordx4 v[174:175], v[234:237], off nt
	s_nop 1
	v_mov_b64_e32 v[182:183], v[176:177]
	s_barrier
	s_cmp_eq_u32 s32, 1
	s_cbranch_scc1 .Lp6_hdr2
	s_branch .Lp6_exit
